# v33 edits (kbar 32 loads in flight, P8 epilogue ssq hoist) plus memory-token rmsnorm gain vectors loaded with the row; list-append atomics change reverted
# baseline (speedup 1.0000x reference)
.LBB0_27:
	global_load_dwordx4 v[12:15], v[32:33], off offset:-3072
	global_load_dwordx4 v[8:11], v[32:33], off offset:-2048
	global_load_dwordx4 v[4:7], v[32:33], off offset:-1024
	global_load_dwordx4 v[0:3], v[32:33], off
	v_add_co_u32_e32 v56, vcc, 0xfffff000, v32
	global_load_dwordx4 v[36:39], v[20:21], off
	s_nop 0
	v_addc_co_u32_e32 v57, vcc, -1, v33, vcc
	global_load_dwordx4 v[40:43], v[56:57], off offset:-3072
	global_load_dwordx4 v[44:47], v[56:57], off offset:-2048
	global_load_dwordx4 v[48:51], v[56:57], off offset:-1024
	global_load_dwordx4 v[52:55], v[32:33], off offset:-4096
	global_load_dwordx4 v[100:103], v[20:21], off offset:1024
	global_load_dwordx4 v[104:107], v[20:21], off offset:2048
	global_load_dwordx4 v[108:111], v[20:21], off offset:3072
	global_load_dwordx4 v[112:115], v[22:23], off
	global_load_dwordx4 v[116:119], v[24:25], off
	global_load_dwordx4 v[120:123], v[26:27], off
	global_load_dwordx4 v[124:127], v[28:29], off
	s_add_i32 s15, s15, s4
	s_cmpk_gt_i32 s15, 0x1ff
	v_lshl_add_u64 v[32:33], v[32:33], 0, s[46:47]
	s_waitcnt vmcnt(15)
	v_mul_f32_e32 v35, v13, v13
	v_mul_f32_e32 v56, v15, v15
	s_waitcnt vmcnt(14)
	v_mul_f32_e32 v57, v9, v9
	v_mul_f32_e32 v58, v11, v11
	s_waitcnt vmcnt(13)
	v_mul_f32_e32 v59, v5, v5
	v_mul_f32_e32 v67, v7, v7
	s_waitcnt vmcnt(12)
	v_mul_f32_e32 v68, v1, v1
	v_mul_f32_e32 v69, v3, v3
	v_fmac_f32_e32 v35, v12, v12
	v_fmac_f32_e32 v56, v14, v14
	v_fmac_f32_e32 v57, v8, v8
	v_fmac_f32_e32 v58, v10, v10
	v_fmac_f32_e32 v59, v4, v4
	v_fmac_f32_e32 v67, v6, v6
	v_fmac_f32_e32 v68, v0, v0
	v_fmac_f32_e32 v69, v2, v2
	s_waitcnt vmcnt(10)
	v_mul_f32_e32 v70, v41, v41
	v_mul_f32_e32 v71, v43, v43
	s_waitcnt vmcnt(9)
	v_mul_f32_e32 v72, v45, v45
	v_mul_f32_e32 v73, v47, v47
	v_add_f32_e32 v35, v35, v56
	s_waitcnt vmcnt(8)
	v_mul_f32_e32 v56, v49, v49
	v_add_f32_e32 v57, v57, v58
	v_mul_f32_e32 v58, v51, v51
	v_add_f32_e32 v59, v59, v67
	s_waitcnt vmcnt(7)
	v_mul_f32_e32 v67, v53, v53
	v_add_f32_e32 v68, v68, v69
	v_mul_f32_e32 v69, v55, v55
	v_fmac_f32_e32 v70, v40, v40
	v_fmac_f32_e32 v71, v42, v42
	v_fmac_f32_e32 v72, v44, v44
	v_fmac_f32_e32 v73, v46, v46
	v_fmac_f32_e32 v56, v48, v48
	v_fmac_f32_e32 v58, v50, v50
	v_fmac_f32_e32 v67, v52, v52
	v_fmac_f32_e32 v69, v54, v54
	v_add_f32_e32 v70, v70, v71
	v_add_f32_e32 v71, v72, v73
	v_add_f32_e32 v56, v56, v58
	v_add_f32_e32 v58, v67, v69
	v_add_f32_e32 v67, v70, v71
	v_add_f32_e32 v56, v67, v56
	v_add_f32_e32 v56, v56, v58
	v_add_f32_e32 v35, v56, v35
	v_add_f32_e32 v35, v35, v57
	v_add_f32_e32 v35, v35, v59
	v_add_f32_e32 v35, v35, v68
	ds_bpermute_b32 v56, v87, v35
	s_waitcnt lgkmcnt(0)
	v_add_f32_e32 v35, v35, v56
	ds_bpermute_b32 v56, v88, v35
	s_waitcnt lgkmcnt(0)
	v_add_f32_e32 v35, v35, v56
	ds_bpermute_b32 v56, v89, v35
	s_waitcnt lgkmcnt(0)
	v_add_f32_e32 v35, v35, v56
	ds_bpermute_b32 v56, v90, v35
	s_waitcnt lgkmcnt(0)
	v_add_f32_e32 v35, v35, v56
	v_mov_b32_e32 v56, v35
	s_nop 1
	v_permlane16_swap_b32_e32 v35, v56
	v_add_f32_e32 v35, v35, v56
	v_mov_b32_e32 v56, v35
	s_nop 1
	v_permlane32_swap_b32_e32 v35, v56
	v_add_f32_e32 v35, v35, v56
	v_fmamk_f32 v35, v35, 0x3a000000, v17
	v_mul_f32_e32 v56, 0x4f800000, v35
	v_cmp_gt_f32_e32 vcc, s5, v35
	s_nop 1
	v_cndmask_b32_e32 v35, v35, v56, vcc
	v_sqrt_f32_e32 v56, v35
	s_nop 0
	v_add_u32_e32 v57, -1, v56
	v_add_u32_e32 v58, 1, v56
	v_fma_f32 v59, -v57, v56, v35
	v_fma_f32 v67, -v58, v56, v35
	v_cmp_ge_f32_e64 s[0:1], 0, v59
	s_nop 1
	v_cndmask_b32_e64 v56, v56, v57, s[0:1]
	v_cmp_lt_f32_e64 s[0:1], 0, v67
	s_nop 1
	v_cndmask_b32_e64 v56, v56, v58, s[0:1]
	v_mul_f32_e32 v57, 0x37800000, v56
	v_cndmask_b32_e32 v56, v56, v57, vcc
	v_cmp_class_f32_e32 vcc, v35, v19
	s_nop 1
	v_cndmask_b32_e32 v35, v56, v35, vcc
	v_div_scale_f32 v56, s[0:1], v35, v35, 1.0
	v_rcp_f32_e32 v58, v56
	v_div_scale_f32 v57, vcc, 1.0, v35, 1.0
	v_fma_f32 v59, -v56, v58, 1.0
	v_fmac_f32_e32 v58, v59, v58
	v_mul_f32_e32 v59, v57, v58
	v_fma_f32 v67, -v56, v59, v57
	v_fmac_f32_e32 v59, v67, v58
	v_fma_f32 v56, -v56, v59, v57
	v_div_fmas_f32 v56, v56, v58, v59
	v_div_fixup_f32 v35, v56, v35, 1.0
	v_mul_f32_e32 v40, v40, v35
	v_mul_f32_e32 v41, v41, v35
	v_mul_f32_e32 v42, v42, v35
	v_mul_f32_e32 v43, v43, v35
	v_mul_f32_e32 v36, v36, v40
	v_mul_f32_e32 v37, v37, v41
	v_mul_f32_e32 v38, v38, v42
	v_mul_f32_e32 v39, v39, v43
	v_cvt_pk_bf16_f32 v36, v36, v37
	v_cvt_pk_bf16_f32 v37, v38, v39
	global_store_dwordx2 v[30:31], v[36:37], off offset:-3584
	s_waitcnt vmcnt(1)
	v_mov_b64_e32 v[36:37], v[100:101]
	v_mov_b64_e32 v[38:39], v[102:103]
	v_mul_f32_e32 v40, v44, v35
	v_mul_f32_e32 v41, v45, v35
	v_mul_f32_e32 v42, v46, v35
	v_mul_f32_e32 v43, v47, v35
	v_mul_f32_e32 v12, v12, v35
	v_mul_f32_e32 v13, v13, v35
	v_mul_f32_e32 v14, v14, v35
	v_mul_f32_e32 v15, v15, v35
	v_mul_f32_e32 v8, v8, v35
	v_mul_f32_e32 v9, v9, v35
	v_mul_f32_e32 v10, v10, v35
	v_mul_f32_e32 v11, v11, v35
	v_mul_f32_e32 v4, v4, v35
	v_mul_f32_e32 v5, v5, v35
	v_mul_f32_e32 v6, v6, v35
	v_mul_f32_e32 v7, v7, v35
	v_mul_f32_e32 v0, v0, v35
	v_mul_f32_e32 v1, v1, v35
	v_mul_f32_e32 v2, v2, v35
	v_mul_f32_e32 v3, v3, v35
	v_mul_f32_e32 v36, v36, v40
	v_mul_f32_e32 v37, v37, v41
	v_mul_f32_e32 v38, v38, v42
	v_mul_f32_e32 v39, v39, v43
	v_cvt_pk_bf16_f32 v36, v36, v37
	v_cvt_pk_bf16_f32 v37, v38, v39
	global_store_dwordx2 v[30:31], v[36:37], off offset:-3072
	v_mov_b64_e32 v[36:37], v[104:105]
	v_mov_b64_e32 v[38:39], v[106:107]
	v_mul_f32_e32 v40, v48, v35
	v_mul_f32_e32 v41, v49, v35
	v_mul_f32_e32 v42, v50, v35
	v_mul_f32_e32 v43, v51, v35
	v_mul_f32_e32 v36, v40, v36
	v_mul_f32_e32 v37, v41, v37
	v_mul_f32_e32 v38, v42, v38
	v_mul_f32_e32 v39, v43, v39
	v_cvt_pk_bf16_f32 v36, v36, v37
	v_cvt_pk_bf16_f32 v37, v38, v39
	global_store_dwordx2 v[30:31], v[36:37], off offset:-2560
	v_mov_b64_e32 v[36:37], v[108:109]
	v_mov_b64_e32 v[38:39], v[110:111]
	v_mul_f32_e32 v40, v52, v35
	v_mul_f32_e32 v41, v53, v35
	v_mul_f32_e32 v42, v54, v35
	v_mul_f32_e32 v43, v55, v35
	v_mul_f32_e32 v36, v40, v36
	v_mul_f32_e32 v37, v41, v37
	v_mul_f32_e32 v38, v42, v38
	v_mul_f32_e32 v39, v43, v39
	v_cvt_pk_bf16_f32 v36, v36, v37
	v_cvt_pk_bf16_f32 v37, v38, v39
	global_store_dwordx2 v[30:31], v[36:37], off offset:-2048
	v_mov_b64_e32 v[36:37], v[112:113]
	v_mov_b64_e32 v[38:39], v[114:115]
	v_mul_f32_e32 v12, v12, v36
	v_mul_f32_e32 v13, v13, v37
	v_mul_f32_e32 v14, v14, v38
	v_mul_f32_e32 v15, v15, v39
	v_cvt_pk_bf16_f32 v12, v12, v13
	v_cvt_pk_bf16_f32 v13, v14, v15
	global_store_dwordx2 v[30:31], v[12:13], off offset:-1536
	v_mov_b64_e32 v[12:13], v[116:117]
	v_mov_b64_e32 v[14:15], v[118:119]
	v_mul_f32_e32 v8, v8, v12
	v_mul_f32_e32 v9, v9, v13
	v_mul_f32_e32 v10, v10, v14
	v_mul_f32_e32 v11, v11, v15
	v_cvt_pk_bf16_f32 v8, v8, v9
	v_cvt_pk_bf16_f32 v9, v10, v11
	global_store_dwordx2 v[30:31], v[8:9], off offset:-1024
	v_mov_b64_e32 v[8:9], v[120:121]
	v_mov_b64_e32 v[10:11], v[122:123]
	v_mul_f32_e32 v4, v4, v8
	v_mul_f32_e32 v5, v5, v9
	v_mul_f32_e32 v6, v6, v10
	v_mul_f32_e32 v7, v7, v11
	v_cvt_pk_bf16_f32 v4, v4, v5
	v_cvt_pk_bf16_f32 v5, v6, v7
	global_store_dwordx2 v[30:31], v[4:5], off offset:-512
	v_mov_b64_e32 v[4:5], v[124:125]
	v_mov_b64_e32 v[6:7], v[126:127]
	v_mul_f32_e32 v0, v0, v4
	v_mul_f32_e32 v1, v1, v5
	v_mul_f32_e32 v2, v2, v6
	v_mul_f32_e32 v3, v3, v7
	v_cvt_pk_bf16_f32 v0, v0, v1
	v_cvt_pk_bf16_f32 v1, v2, v3
	global_store_dwordx2 v[30:31], v[0:1], off
	v_lshl_add_u64 v[30:31], v[30:31], 0, s[44:45]
	s_cbranch_scc0 .LBB0_27
